# A/B of the attention-phase static priority raise: waves 0-3 raised instead of waves 4-7
# speedup vs baseline: 1.0078x; 1.0078x over previous
; #define LAS __attribute__((address_space(3)))
; __global__ void __launch_bounds__(NTHREADS, 2) fwd_kernel(Args a) {
;     ...
;         else if (k == 1) {
;             const int lane = ltid & 63;
;             LAS float* redbase = (LAS float*)lds;
;             LAS float* rpl = (LAS float*)(lds + 4096 + wave * 4096 + 256);
;             const int ql = lane & 31, hi = lane >> 5, w = wave;
;             {
;                 const float* rp = rpb + ((size_t)layer * 8 + w) * (15 * 31);
;                 for (int i = lane; i < 15 * 31; i += 64) rpl[i] = rp[i] * LOG2E;
;                 asm volatile("s_waitcnt lgkmcnt(0)" ::: "memory");
;             }
;             int ucount = 0;
; #pragma unroll 1
;             for (int u0 = bid; u0 < 512; u0 += G, ++ucount) {
.LBB0_133:
	s_cmp_gt_i32 s16, 0
	s_mov_b64 s[10:11], -1
	s_cbranch_scc0 .LBB0_168
	v_readlane_b32 s60, v238, 0
	s_lshl_b32 s14, s50, 3
	v_readlane_b32 s8, v238, 20
	v_readlane_b32 s64, v238, 4
	v_readlane_b32 s65, v238, 5
	s_add_i32 s14, s14, s8
	s_cmp_lt_u32 s8, 4
	s_cbranch_scc0 .Lattn_prio_done
	s_setprio 1
